# GEMM K-loop back edge: next iteration's scalar address setup moved in front of the loop-back barrier
# baseline (speedup 1.0000x reference)
; #define PG8_STAGE(bufoff, gbase, voff) do { _Pragma("unroll") for (int _i = 0; _i < 2; ++_i) \
;         __builtin_amdgcn_global_load_lds((const unsigned*)((const char*)(gbase) + (voff)[_i]), (LAS unsigned*)(lds + (bufoff) + ldsw + _i * 8192), 16, 0, 0); } while (0)
; #define PG8_LDA(dst, b, h) do { _Pragma("unroll") for (int m = 0; m < 4; ++m) _Pragma("unroll") for (int k = 0; k < 2; ++k) dst[m][k] = *(const LAS bf16x8*)(lds + PG8_SA(b, h) + aoff + m * 2048 + k * 1024); } while (0)
; #define PG8_LDB(dst, b, h) do { _Pragma("unroll") for (int n = 0; n < 2; ++n) _Pragma("unroll") for (int k = 0; k < 2; ++k) dst[n][k] = *(const LAS bf16x8*)(lds + PG8_SB(b, h) + boff + n * 2048 + k * 1024); } while (0)
; #define PG8_MMA(ai, bj, At, Bt) do { __builtin_amdgcn_s_setprio(1); _Pragma("unroll") for (int m = 0; m < 4; ++m) _Pragma("unroll") for (int n = 0; n < 2; ++n) _Pragma("unroll") for (int k = 0; k < 2; ++k) \
;         acc[ai][bj][m][n] = __builtin_amdgcn_mfma_f32_16x16x32_bf16(Bt[n][k], At[m][k], acc[ai][bj][m][n], 0, 0, 0); __builtin_amdgcn_s_setprio(0); } while (0)
; #define PG8_WAIT_V(n) asm volatile("s_waitcnt vmcnt(" #n ")" ::: "memory")
; #define PG8_WAIT_L(n) asm volatile("s_waitcnt lgkmcnt(" #n ")" ::: "memory")
; template <class Epi>
; __device__ __forceinline__ void gemm_phase(LAS unsigned char* lds, const Gemm g, const StaticOrder& S, const Epi& E) {
;     ...
;         for (int t = 0; t < nt; t += 2) {
;             const bool last = (t == nt - 2);
;             const char* a1 = cA + (size_t)(t + 1) * kstep;
;             const char* a2 = last ? nA : cA + (size_t)(t + 2) * kstep; const char* b2 = last ? nB : cB + (size_t)(t + 2) * kstep;
;             const char* a3 = a2 + kstep; const char* b3 = b2 + kstep;
;             PG8_LDB(B0, 0, 0); PG8_SCHED; PG8_LDA(At, 0, 0); PG8_STAGE(PG8_SA(1, 1), a1 + hstepA, voffA);
;             PG8_WAIT_L(8); PG8_BAR; PG8_WAIT_L(0); PG8_MMA(0, 0, At, B0); PG8_BAR; PG8_SCHED;
;             PG8_LDB(B1, 0, 1); PG8_STAGE(PG8_SB(0, 0), b2, voffB);
;             PG8_BAR; PG8_WAIT_L(0); PG8_MMA(0, 1, At, B1); PG8_BAR;
;             PG8_LDA(At, 0, 1); PG8_STAGE(PG8_SA(0, 0), a2, voffA);
;             PG8_BAR; PG8_WAIT_L(0); PG8_MMA(1, 0, At, B0); PG8_BAR; PG8_SCHED;
;             PG8_STAGE(PG8_SB(0, 1), b2 + hstepB, voffB);
;             PG8_WAIT_V(6); PG8_BAR; PG8_MMA(1, 1, At, B1); PG8_BAR;
.Lk_body:
	ds_read_b128 v[132:135], v144
	ds_read_b128 v[136:139], v144 offset:1024
	ds_read_b128 v[140:143], v144 offset:2048
	ds_read_b128 v[144:147], v144 offset:3072
	s_cmpk_eq_i32 s64, 0x700
	s_cselect_b32 s69, s61, s11
	s_cselect_b32 s68, s60, s10
	s_cselect_b32 s67, s59, s67
	s_cselect_b32 s66, s58, s66
	s_add_i32 m0, s12, 0xc000
	ds_read_b128 v[148:151], v241
	ds_read_b128 v[152:155], v241 offset:1024
	ds_read_b128 v[156:159], v241 offset:2048
	ds_read_b128 v[160:163], v241 offset:3072
	ds_read_b128 v[164:167], v241 offset:4096
	ds_read_b128 v[168:171], v241 offset:5120
	ds_read_b128 v[172:175], v241 offset:6144
	ds_read_b128 v[192:195], v241 offset:7168
	global_load_lds_dwordx4 v190, s[100:101]
	s_add_i32 m0, s12, 0xe000
	s_nop 0
	global_load_lds_dwordx4 v188, s[100:101]
	s_waitcnt lgkmcnt(8)
	s_barrier
	s_waitcnt lgkmcnt(0)
	s_waitcnt lgkmcnt(0)
	v_mfma_f32_16x16x32_bf16 v[124:127], v[132:135], v[148:151], v[124:127]
	v_mfma_f32_16x16x32_bf16 v[120:123], v[140:143], v[148:151], v[120:123]
	v_mfma_f32_16x16x32_bf16 v[116:119], v[132:135], v[156:159], v[116:119]
	v_mfma_f32_16x16x32_bf16 v[112:115], v[140:143], v[156:159], v[112:115]
	v_mfma_f32_16x16x32_bf16 v[108:111], v[132:135], v[164:167], v[108:111]
	v_mfma_f32_16x16x32_bf16 v[104:107], v[140:143], v[164:167], v[104:107]
	v_mfma_f32_16x16x32_bf16 v[100:103], v[132:135], v[172:175], v[100:103]
	v_mfma_f32_16x16x32_bf16 v[96:99], v[140:143], v[172:175], v[96:99]
	v_mfma_f32_16x16x32_bf16 v[124:127], v[136:139], v[152:155], v[124:127]
	v_mfma_f32_16x16x32_bf16 v[120:123], v[144:147], v[152:155], v[120:123]
	v_mfma_f32_16x16x32_bf16 v[116:119], v[136:139], v[160:163], v[116:119]
	v_mfma_f32_16x16x32_bf16 v[112:115], v[144:147], v[160:163], v[112:115]
	v_mfma_f32_16x16x32_bf16 v[108:111], v[136:139], v[168:171], v[108:111]
	v_mfma_f32_16x16x32_bf16 v[104:107], v[144:147], v[168:171], v[104:107]
	v_mfma_f32_16x16x32_bf16 v[100:103], v[136:139], v[192:195], v[100:103]
	v_mfma_f32_16x16x32_bf16 v[96:99], v[144:147], v[192:195], v[96:99]
	s_barrier
	s_add_i32 s40, 0, 0x14000
	s_add_i32 s10, s72, s57
	v_add_u32_e32 v176, s40, v252
	s_mov_b32 m0, s10
	ds_read_b128 v[196:199], v176
	ds_read_b128 v[200:203], v176 offset:1024
	ds_read_b128 v[204:207], v176 offset:2048
	ds_read_b128 v[208:211], v176 offset:3072
	global_load_lds_dwordx4 v182, s[66:67]
	s_add_i32 m0, s10, 0x2000
	s_nop 0
	global_load_lds_dwordx4 v186, s[66:67]
	s_barrier
	s_waitcnt lgkmcnt(0)
	s_waitcnt lgkmcnt(0)
	v_mfma_f32_16x16x32_bf16 v[60:63], v[196:199], v[148:151], v[60:63]
	v_mfma_f32_16x16x32_bf16 v[56:59], v[204:207], v[148:151], v[56:59]
	v_mfma_f32_16x16x32_bf16 v[52:55], v[196:199], v[156:159], v[52:55]
	v_mfma_f32_16x16x32_bf16 v[48:51], v[204:207], v[156:159], v[48:51]
	v_mfma_f32_16x16x32_bf16 v[44:47], v[196:199], v[164:167], v[44:47]
	v_mfma_f32_16x16x32_bf16 v[40:43], v[204:207], v[164:167], v[40:43]
	v_mfma_f32_16x16x32_bf16 v[36:39], v[196:199], v[172:175], v[36:39]
	v_mfma_f32_16x16x32_bf16 v[32:35], v[204:207], v[172:175], v[32:35]
	v_mfma_f32_16x16x32_bf16 v[60:63], v[200:203], v[152:155], v[60:63]
	v_mfma_f32_16x16x32_bf16 v[56:59], v[208:211], v[152:155], v[56:59]
	v_mfma_f32_16x16x32_bf16 v[52:55], v[200:203], v[160:163], v[52:55]
	v_mfma_f32_16x16x32_bf16 v[48:51], v[208:211], v[160:163], v[48:51]
	v_mfma_f32_16x16x32_bf16 v[44:47], v[200:203], v[168:171], v[44:47]
	v_mfma_f32_16x16x32_bf16 v[40:43], v[208:211], v[168:171], v[40:43]
	v_mfma_f32_16x16x32_bf16 v[36:39], v[200:203], v[192:195], v[36:39]
	v_mfma_f32_16x16x32_bf16 v[32:35], v[208:211], v[192:195], v[32:35]
	s_mov_b32 m0, s12
	s_barrier
	ds_read_b128 v[148:151], v241 offset:16384
	ds_read_b128 v[152:155], v241 offset:17408
	ds_read_b128 v[156:159], v241 offset:18432
	ds_read_b128 v[160:163], v241 offset:19456
	ds_read_b128 v[164:167], v241 offset:20480
	ds_read_b128 v[168:171], v241 offset:21504
	ds_read_b128 v[172:175], v241 offset:22528
	ds_read_b128 v[192:195], v241 offset:23552
	global_load_lds_dwordx4 v180, s[68:69]
	s_mov_b32 m0, s13
	s_nop 0
	global_load_lds_dwordx4 v184, s[68:69]
	s_barrier
	s_waitcnt lgkmcnt(0)
	s_waitcnt lgkmcnt(0)
	v_mfma_f32_16x16x32_bf16 v[92:95], v[132:135], v[148:151], v[92:95]
	v_mfma_f32_16x16x32_bf16 v[88:91], v[140:143], v[148:151], v[88:91]
	v_mfma_f32_16x16x32_bf16 v[84:87], v[132:135], v[156:159], v[84:87]
	v_mfma_f32_16x16x32_bf16 v[80:83], v[140:143], v[156:159], v[80:83]
	v_mfma_f32_16x16x32_bf16 v[76:79], v[132:135], v[164:167], v[76:79]
	v_mfma_f32_16x16x32_bf16 v[72:75], v[140:143], v[164:167], v[72:75]
	v_mfma_f32_16x16x32_bf16 v[68:71], v[132:135], v[172:175], v[68:71]
	v_mfma_f32_16x16x32_bf16 v[64:67], v[140:143], v[172:175], v[64:67]
	v_mfma_f32_16x16x32_bf16 v[92:95], v[136:139], v[152:155], v[92:95]
	v_mfma_f32_16x16x32_bf16 v[88:91], v[144:147], v[152:155], v[88:91]
	v_mfma_f32_16x16x32_bf16 v[84:87], v[136:139], v[160:163], v[84:87]
	v_mfma_f32_16x16x32_bf16 v[80:83], v[144:147], v[160:163], v[80:83]
	v_mfma_f32_16x16x32_bf16 v[76:79], v[136:139], v[168:171], v[76:79]
	v_mfma_f32_16x16x32_bf16 v[72:75], v[144:147], v[168:171], v[72:75]
	v_mfma_f32_16x16x32_bf16 v[68:71], v[136:139], v[192:195], v[68:71]
	v_mfma_f32_16x16x32_bf16 v[64:67], v[144:147], v[192:195], v[64:67]
	s_barrier
	s_add_u32 s10, s66, 0x40000
	s_addc_u32 s11, s67, 0
	s_add_i32 s40, s40, s57
	s_mov_b32 m0, s40
	s_nop 0
	global_load_lds_dwordx4 v182, s[10:11]
	s_add_i32 m0, s40, 0x2000
	s_nop 0
	global_load_lds_dwordx4 v186, s[10:11]
	s_waitcnt vmcnt(6)
	s_barrier
; #define PG8_STAGE(bufoff, gbase, voff) do { _Pragma("unroll") for (int _i = 0; _i < 2; ++_i) \
;         __builtin_amdgcn_global_load_lds((const unsigned*)((const char*)(gbase) + (voff)[_i]), (LAS unsigned*)(lds + (bufoff) + ldsw + _i * 8192), 16, 0, 0); } while (0)
; #define PG8_LDA(dst, b, h) do { _Pragma("unroll") for (int m = 0; m < 4; ++m) _Pragma("unroll") for (int k = 0; k < 2; ++k) dst[m][k] = *(const LAS bf16x8*)(lds + PG8_SA(b, h) + aoff + m * 2048 + k * 1024); } while (0)
; #define PG8_LDB(dst, b, h) do { _Pragma("unroll") for (int n = 0; n < 2; ++n) _Pragma("unroll") for (int k = 0; k < 2; ++k) dst[n][k] = *(const LAS bf16x8*)(lds + PG8_SB(b, h) + boff + n * 2048 + k * 1024); } while (0)
; #define PG8_MMA(ai, bj, At, Bt) do { __builtin_amdgcn_s_setprio(1); _Pragma("unroll") for (int m = 0; m < 4; ++m) _Pragma("unroll") for (int n = 0; n < 2; ++n) _Pragma("unroll") for (int k = 0; k < 2; ++k) \
;         acc[ai][bj][m][n] = __builtin_amdgcn_mfma_f32_16x16x32_bf16(Bt[n][k], At[m][k], acc[ai][bj][m][n], 0, 0, 0); __builtin_amdgcn_s_setprio(0); } while (0)
; #define PG8_WAIT_V(n) asm volatile("s_waitcnt vmcnt(" #n ")" ::: "memory")
; #define PG8_WAIT_L(n) asm volatile("s_waitcnt lgkmcnt(" #n ")" ::: "memory")
; #define PG8_BAR __builtin_amdgcn_s_barrier()
; #define PG8_SCHED __builtin_amdgcn_sched_barrier(0)
; template <class Epi>
; __device__ __forceinline__ void gemm_phase(LAS unsigned char* lds, const Gemm g, const StaticOrder& S, const Epi& E) {
;     ...
;             PG8_WAIT_V(6); PG8_BAR; PG8_MMA(1, 1, At, B1); PG8_BAR;
;             PG8_LDB(B0, 1, 0); PG8_SCHED; PG8_LDA(At, 1, 0); PG8_STAGE(PG8_SA(0, 1), a2 + hstepA, voffA);
;             PG8_WAIT_L(8); PG8_BAR; PG8_WAIT_L(0); PG8_MMA(0, 0, At, B0); PG8_BAR; PG8_SCHED;
;             PG8_LDB(B1, 1, 1); PG8_STAGE(PG8_SB(1, 0), b3, voffB);
;             PG8_BAR; PG8_WAIT_L(0); PG8_MMA(0, 1, At, B1); PG8_BAR;
;             PG8_LDA(At, 1, 1); PG8_STAGE(PG8_SA(1, 0), a3, voffA);
;             PG8_BAR; PG8_WAIT_L(0); PG8_MMA(1, 0, At, B0); PG8_BAR; PG8_SCHED;
	v_mfma_f32_16x16x32_bf16 v[28:31], v[196:199], v[148:151], v[28:31]
	v_mfma_f32_16x16x32_bf16 v[24:27], v[204:207], v[148:151], v[24:27]
	v_mfma_f32_16x16x32_bf16 v[20:23], v[196:199], v[156:159], v[20:23]
	v_mfma_f32_16x16x32_bf16 v[16:19], v[204:207], v[156:159], v[16:19]
	v_mfma_f32_16x16x32_bf16 v[12:15], v[196:199], v[164:167], v[12:15]
	v_mfma_f32_16x16x32_bf16 v[8:11], v[204:207], v[164:167], v[8:11]
	v_mfma_f32_16x16x32_bf16 v[4:7], v[196:199], v[172:175], v[4:7]
	v_mfma_f32_16x16x32_bf16 v[0:3], v[204:207], v[172:175], v[0:3]
	v_mfma_f32_16x16x32_bf16 v[28:31], v[200:203], v[152:155], v[28:31]
	v_mfma_f32_16x16x32_bf16 v[24:27], v[208:211], v[152:155], v[24:27]
	v_mfma_f32_16x16x32_bf16 v[20:23], v[200:203], v[160:163], v[20:23]
	v_mfma_f32_16x16x32_bf16 v[16:19], v[208:211], v[160:163], v[16:19]
	v_mfma_f32_16x16x32_bf16 v[12:15], v[200:203], v[168:171], v[12:15]
	v_mfma_f32_16x16x32_bf16 v[8:11], v[208:211], v[168:171], v[8:11]
	v_mfma_f32_16x16x32_bf16 v[4:7], v[200:203], v[192:195], v[4:7]
	v_mfma_f32_16x16x32_bf16 v[0:3], v[208:211], v[192:195], v[0:3]
	s_add_i32 s40, 0, 0x18000
	v_add_u32_e32 v144, s40, v252
	s_barrier
	ds_read_b128 v[132:135], v144
	ds_read_b128 v[136:139], v144 offset:1024
	ds_read_b128 v[140:143], v144 offset:2048
	ds_read_b128 v[144:147], v144 offset:3072
	s_add_u32 s10, s68, s54
	s_addc_u32 s11, s69, 0
	s_mov_b32 m0, s4
	ds_read_b128 v[148:151], v241 offset:32768
	ds_read_b128 v[152:155], v241 offset:33792
	ds_read_b128 v[156:159], v241 offset:34816
	ds_read_b128 v[160:163], v241 offset:35840
	ds_read_b128 v[164:167], v241 offset:36864
	ds_read_b128 v[168:171], v241 offset:37888
	ds_read_b128 v[172:175], v241 offset:38912
	ds_read_b128 v[192:195], v241 offset:39936
	global_load_lds_dwordx4 v180, s[10:11]
	s_mov_b32 m0, s70
	s_nop 0
	global_load_lds_dwordx4 v184, s[10:11]
	s_waitcnt lgkmcnt(8)
	s_barrier
	s_waitcnt lgkmcnt(0)
	s_waitcnt lgkmcnt(0)
	v_mfma_f32_16x16x32_bf16 v[124:127], v[132:135], v[148:151], v[124:127]
	v_mfma_f32_16x16x32_bf16 v[120:123], v[140:143], v[148:151], v[120:123]
	v_mfma_f32_16x16x32_bf16 v[116:119], v[132:135], v[156:159], v[116:119]
	v_mfma_f32_16x16x32_bf16 v[112:115], v[140:143], v[156:159], v[112:115]
	v_mfma_f32_16x16x32_bf16 v[108:111], v[132:135], v[164:167], v[108:111]
	v_mfma_f32_16x16x32_bf16 v[104:107], v[140:143], v[164:167], v[104:107]
	v_mfma_f32_16x16x32_bf16 v[100:103], v[132:135], v[172:175], v[100:103]
	v_mfma_f32_16x16x32_bf16 v[96:99], v[140:143], v[172:175], v[96:99]
	v_mfma_f32_16x16x32_bf16 v[124:127], v[136:139], v[152:155], v[124:127]
	v_mfma_f32_16x16x32_bf16 v[120:123], v[144:147], v[152:155], v[120:123]
	v_mfma_f32_16x16x32_bf16 v[116:119], v[136:139], v[160:163], v[116:119]
	v_mfma_f32_16x16x32_bf16 v[112:115], v[144:147], v[160:163], v[112:115]
	v_mfma_f32_16x16x32_bf16 v[108:111], v[136:139], v[168:171], v[108:111]
	v_mfma_f32_16x16x32_bf16 v[104:107], v[144:147], v[168:171], v[104:107]
	v_mfma_f32_16x16x32_bf16 v[100:103], v[136:139], v[192:195], v[100:103]
	v_mfma_f32_16x16x32_bf16 v[96:99], v[144:147], v[192:195], v[96:99]
	s_barrier
	s_add_i32 s41, 0, 0x1c000
	s_add_i32 s10, s40, s57
	v_add_u32_e32 v176, s41, v252
	s_add_u32 s100, s66, 0x80
	s_addc_u32 s101, s67, 0
	s_mov_b32 m0, s10
	ds_read_b128 v[196:199], v176
	ds_read_b128 v[200:203], v176 offset:1024
	ds_read_b128 v[204:207], v176 offset:2048
	ds_read_b128 v[208:211], v176 offset:3072
	global_load_lds_dwordx4 v182, s[100:101]
	s_add_i32 m0, s10, 0x2000
	s_nop 0
	global_load_lds_dwordx4 v186, s[100:101]
	s_barrier
	s_waitcnt lgkmcnt(0)
	s_waitcnt lgkmcnt(0)
	v_mfma_f32_16x16x32_bf16 v[60:63], v[196:199], v[148:151], v[60:63]
	v_mfma_f32_16x16x32_bf16 v[56:59], v[204:207], v[148:151], v[56:59]
	v_mfma_f32_16x16x32_bf16 v[52:55], v[196:199], v[156:159], v[52:55]
	v_mfma_f32_16x16x32_bf16 v[48:51], v[204:207], v[156:159], v[48:51]
	v_mfma_f32_16x16x32_bf16 v[44:47], v[196:199], v[164:167], v[44:47]
	v_mfma_f32_16x16x32_bf16 v[40:43], v[204:207], v[164:167], v[40:43]
	v_mfma_f32_16x16x32_bf16 v[36:39], v[196:199], v[172:175], v[36:39]
	v_mfma_f32_16x16x32_bf16 v[32:35], v[204:207], v[172:175], v[32:35]
	v_mfma_f32_16x16x32_bf16 v[60:63], v[200:203], v[152:155], v[60:63]
	v_mfma_f32_16x16x32_bf16 v[56:59], v[208:211], v[152:155], v[56:59]
	v_mfma_f32_16x16x32_bf16 v[52:55], v[200:203], v[160:163], v[52:55]
	v_mfma_f32_16x16x32_bf16 v[48:51], v[208:211], v[160:163], v[48:51]
	v_mfma_f32_16x16x32_bf16 v[44:47], v[200:203], v[168:171], v[44:47]
	v_mfma_f32_16x16x32_bf16 v[40:43], v[208:211], v[168:171], v[40:43]
	v_mfma_f32_16x16x32_bf16 v[36:39], v[200:203], v[192:195], v[36:39]
	v_mfma_f32_16x16x32_bf16 v[32:35], v[208:211], v[192:195], v[32:35]
	s_mov_b32 m0, s6
	s_add_u32 s100, s68, 0x80
	s_addc_u32 s101, s69, 0
	s_barrier
	ds_read_b128 v[148:151], v241 offset:49152
	ds_read_b128 v[152:155], v241 offset:50176
	ds_read_b128 v[156:159], v241 offset:51200
	ds_read_b128 v[160:163], v241 offset:52224
	ds_read_b128 v[164:167], v241 offset:53248
	ds_read_b128 v[168:171], v241 offset:54272
	ds_read_b128 v[172:175], v241 offset:55296
	ds_read_b128 v[192:195], v241 offset:56320
	global_load_lds_dwordx4 v180, s[100:101]
	s_mov_b32 m0, s78
	s_nop 0
	global_load_lds_dwordx4 v184, s[100:101]
	s_barrier
; __device__ __forceinline__ float bf_lo(unsigned u) { return __uint_as_float(u << 16); }
; __device__ __forceinline__ float bf_hi(unsigned u) { return __uint_as_float(u & 0xffff0000u); }
; #define PG8_STAGE(bufoff, gbase, voff) do { _Pragma("unroll") for (int _i = 0; _i < 2; ++_i) \
;         __builtin_amdgcn_global_load_lds((const unsigned*)((const char*)(gbase) + (voff)[_i]), (LAS unsigned*)(lds + (bufoff) + ldsw + _i * 8192), 16, 0, 0); } while (0)
; #define PG8_MMA(ai, bj, At, Bt) do { __builtin_amdgcn_s_setprio(1); _Pragma("unroll") for (int m = 0; m < 4; ++m) _Pragma("unroll") for (int n = 0; n < 2; ++n) _Pragma("unroll") for (int k = 0; k < 2; ++k) \
;         acc[ai][bj][m][n] = __builtin_amdgcn_mfma_f32_16x16x32_bf16(Bt[n][k], At[m][k], acc[ai][bj][m][n], 0, 0, 0); __builtin_amdgcn_s_setprio(0); } while (0)
; #define PG8_WAIT_V(n) asm volatile("s_waitcnt vmcnt(" #n ")" ::: "memory")
; #define PG8_WAIT_L(n) asm volatile("s_waitcnt lgkmcnt(" #n ")" ::: "memory")
; #define PG8_BAR __builtin_amdgcn_s_barrier()
; template <class Epi>
; __device__ __forceinline__ void gemm_phase(LAS unsigned char* lds, const Gemm g, const StaticOrder& S, const Epi& E) {
;     ...
;             PG8_BAR; PG8_WAIT_L(0); PG8_MMA(1, 0, At, B0); PG8_BAR; PG8_SCHED;
;             PG8_STAGE(PG8_SB(1, 1), b3 + hstepB, voffB);
;             PG8_WAIT_V(6); PG8_BAR; PG8_MMA(1, 1, At, B1); PG8_BAR;
;         }
;         if (!lastpass) { E.mid(acc, cur, wr, wc, fr, fq); cA = nA; cB = nB; }
;     __device__ __forceinline__ void mid(f32x4 (&acc)[2][2][4][2], const pg8::Unit& u, int wr, int wc, int fr_in, int fq_in) const {
;         int fr = fr_in, fq = fq_in; asm volatile("" : "+v"(fr), "+v"(fq));
;         const int row0 = u.pm * 256 + wr * 64 + fr, col0 = u.pn * 256 + wc * 32 + 8 * fq;
; #pragma unroll
;         for (int i = 0; i < 16; ++i) { const int ai = i >> 3, m = (i >> 1) & 3, bj = i & 1; const int n = col0 + bj * 128;
;             const u32x4 gq = *(const u32x4*)(proj + (size_t)(row0 + ai * 128 + m * 16) * NC1 + C_MG + (n >> 7) * 256 + (n & 127));
;             acc[ai][bj][m][0][0] *= bf_lo(gq.x); acc[ai][bj][m][0][1] *= bf_hi(gq.x); acc[ai][bj][m][0][2] *= bf_lo(gq.y); acc[ai][bj][m][0][3] *= bf_hi(gq.y);
;             acc[ai][bj][m][1][0] *= bf_lo(gq.z); acc[ai][bj][m][1][1] *= bf_hi(gq.z); acc[ai][bj][m][1][2] *= bf_lo(gq.w); acc[ai][bj][m][1][3] *= bf_hi(gq.w); }
	s_waitcnt lgkmcnt(0)
	s_waitcnt lgkmcnt(0)
	v_mfma_f32_16x16x32_bf16 v[92:95], v[132:135], v[148:151], v[92:95]
	v_mfma_f32_16x16x32_bf16 v[88:91], v[140:143], v[148:151], v[88:91]
	v_mfma_f32_16x16x32_bf16 v[84:87], v[132:135], v[156:159], v[84:87]
	v_mfma_f32_16x16x32_bf16 v[80:83], v[140:143], v[156:159], v[80:83]
	v_mfma_f32_16x16x32_bf16 v[76:79], v[132:135], v[164:167], v[76:79]
	v_mfma_f32_16x16x32_bf16 v[72:75], v[140:143], v[164:167], v[72:75]
	v_mfma_f32_16x16x32_bf16 v[68:71], v[132:135], v[172:175], v[68:71]
	v_mfma_f32_16x16x32_bf16 v[64:67], v[140:143], v[172:175], v[64:67]
	v_mfma_f32_16x16x32_bf16 v[92:95], v[136:139], v[152:155], v[92:95]
	v_mfma_f32_16x16x32_bf16 v[88:91], v[144:147], v[152:155], v[88:91]
	v_mfma_f32_16x16x32_bf16 v[84:87], v[136:139], v[160:163], v[84:87]
	v_mfma_f32_16x16x32_bf16 v[80:83], v[144:147], v[160:163], v[80:83]
	v_mfma_f32_16x16x32_bf16 v[76:79], v[136:139], v[168:171], v[76:79]
	v_mfma_f32_16x16x32_bf16 v[72:75], v[144:147], v[168:171], v[72:75]
	v_mfma_f32_16x16x32_bf16 v[68:71], v[136:139], v[192:195], v[68:71]
	v_mfma_f32_16x16x32_bf16 v[64:67], v[144:147], v[192:195], v[64:67]
	s_barrier
	s_add_u32 s10, s66, 0x40080
	s_addc_u32 s11, s67, 0
	s_add_i32 s40, s41, s57
	s_mov_b32 m0, s40
	s_nop 0
	global_load_lds_dwordx4 v182, s[10:11]
	s_add_i32 m0, s40, 0x2000
	s_nop 0
	global_load_lds_dwordx4 v186, s[10:11]
	s_waitcnt vmcnt(6)
	s_barrier
	v_mfma_f32_16x16x32_bf16 v[28:31], v[196:199], v[148:151], v[28:31]
	v_mfma_f32_16x16x32_bf16 v[24:27], v[204:207], v[148:151], v[24:27]
	v_mfma_f32_16x16x32_bf16 v[20:23], v[196:199], v[156:159], v[20:23]
	v_mfma_f32_16x16x32_bf16 v[16:19], v[204:207], v[156:159], v[16:19]
	v_mfma_f32_16x16x32_bf16 v[12:15], v[196:199], v[164:167], v[12:15]
	v_mfma_f32_16x16x32_bf16 v[8:11], v[204:207], v[164:167], v[8:11]
	v_mfma_f32_16x16x32_bf16 v[4:7], v[196:199], v[172:175], v[4:7]
	v_mfma_f32_16x16x32_bf16 v[0:3], v[204:207], v[172:175], v[0:3]
	v_mfma_f32_16x16x32_bf16 v[28:31], v[200:203], v[152:155], v[28:31]
	v_mfma_f32_16x16x32_bf16 v[24:27], v[208:211], v[152:155], v[24:27]
	v_mfma_f32_16x16x32_bf16 v[20:23], v[200:203], v[160:163], v[20:23]
	v_mfma_f32_16x16x32_bf16 v[16:19], v[208:211], v[160:163], v[16:19]
	v_mfma_f32_16x16x32_bf16 v[12:15], v[200:203], v[168:171], v[12:15]
	v_mfma_f32_16x16x32_bf16 v[8:11], v[208:211], v[168:171], v[8:11]
	v_mfma_f32_16x16x32_bf16 v[4:7], v[200:203], v[192:195], v[4:7]
	v_mfma_f32_16x16x32_bf16 v[0:3], v[208:211], v[192:195], v[0:3]
	s_add_i32 s77, s77, 2
	s_add_u32 s64, s64, 0x100
	s_addc_u32 s65, s65, 0
	s_add_u32 s10, s46, s64
	s_addc_u32 s11, s47, s65
	s_add_u32 s100, s10, 0x80
	s_addc_u32 s101, s11, 0
	s_add_u32 s10, s10, 0x100
	s_addc_u32 s11, s11, 0
	s_add_u32 s66, vcc_lo, s64
	s_addc_u32 s67, vcc_hi, s65
	s_add_i32 s72, 0, 0x10000
	v_add_u32_e32 v144, s72, v252
	s_cmp_gt_u32 s77, 13
	s_barrier
	s_cbranch_scc0 .Lk_body
	s_add_u32 s64, vcc_lo, 0xffffff00
	s_addc_u32 s65, vcc_hi, -1
	s_and_b64 vcc, exec, s[62:63]
	s_cbranch_vccz .LBB0_300
	v_mov_b32_e32 v128, v251
	v_mov_b32_e32 v129, v179
	v_mov_b64_e32 v[130:131], s[98:99]
	v_lshl_add_u32 v128, v128, 3, s16
	v_lshlrev_b32_e32 v132, 1, v128
	v_add_u32_e32 v134, s15, v129
	v_and_b32_e32 v140, 0xffffff00, v132
	v_and_b32_e32 v135, 0x78, v128
	v_mad_i64_i32 v[128:129], s[10:11], v134, s22, v[130:131]
	v_ashrrev_i32_e32 v141, 31, v140
	v_lshl_add_u64 v[128:129], v[128:129], 0, s[34:35]
	v_lshlrev_b64 v[132:133], 1, v[140:141]
	v_lshlrev_b32_e32 v176, 1, v135
	v_lshl_add_u64 v[128:129], v[128:129], 0, v[132:133]
	v_lshl_add_u64 v[128:129], v[128:129], 0, v[176:177]
	s_mov_b64 s[64:65], s[44:45]
	s_mov_b64 s[46:47], s[0:1]
	s_mov_b64 s[100:101], 0x50000
	global_load_dwordx4 v[132:135], v[128:129], off
	global_load_dwordx4 v[136:139], v[128:129], off offset:512
	v_lshl_add_u64 v[130:131], v[128:129], 0, s[100:101]
	global_load_dwordx4 v[140:143], v[130:131], off
	global_load_dwordx4 v[144:147], v[130:131], off offset:512
	v_lshl_add_u64 v[130:131], v[130:131], 0, s[100:101]
	global_load_dwordx4 v[148:151], v[130:131], off
	global_load_dwordx4 v[152:155], v[130:131], off offset:512
	v_lshl_add_u64 v[130:131], v[130:131], 0, s[100:101]
	global_load_dwordx4 v[156:159], v[130:131], off
	global_load_dwordx4 v[160:163], v[130:131], off offset:512
	s_mov_b64 s[100:101], 0x280000
	v_lshl_add_u64 v[130:131], v[128:129], 0, s[100:101]
	s_mov_b64 s[100:101], 0x50000
	global_load_dwordx4 v[164:167], v[130:131], off
	global_load_dwordx4 v[168:171], v[130:131], off offset:512
	v_lshl_add_u64 v[130:131], v[130:131], 0, s[100:101]
	global_load_dwordx4 v[172:175], v[130:131], off
	global_load_dwordx4 v[192:195], v[130:131], off offset:512
	v_lshl_add_u64 v[130:131], v[130:131], 0, s[100:101]
	global_load_dwordx4 v[196:199], v[130:131], off
	global_load_dwordx4 v[200:203], v[130:131], off offset:512
	v_lshl_add_u64 v[130:131], v[130:131], 0, s[100:101]
	global_load_dwordx4 v[204:207], v[130:131], off
	global_load_dwordx4 v[208:211], v[130:131], off offset:512
	s_waitcnt vmcnt(15)
	v_lshlrev_b32_e32 v128, 16, v132
	v_and_b32_e32 v129, 0xffff0000, v132
	v_lshlrev_b32_e32 v130, 16, v133
	v_and_b32_e32 v131, 0xffff0000, v133
	v_pk_mul_f32 v[124:125], v[124:125], v[128:129]
	v_pk_mul_f32 v[126:127], v[126:127], v[130:131]
	v_lshlrev_b32_e32 v128, 16, v134
	v_and_b32_e32 v129, 0xffff0000, v134
	v_lshlrev_b32_e32 v130, 16, v135
	v_and_b32_e32 v131, 0xffff0000, v135
	v_pk_mul_f32 v[120:121], v[120:121], v[128:129]
	v_pk_mul_f32 v[122:123], v[122:123], v[130:131]
	s_waitcnt vmcnt(14)
; __device__ __forceinline__ float bf_lo(unsigned u) { return __uint_as_float(u << 16); }
; __device__ __forceinline__ float bf_hi(unsigned u) { return __uint_as_float(u & 0xffff0000u); }
;     __device__ __forceinline__ void mid(f32x4 (&acc)[2][2][4][2], const pg8::Unit& u, int wr, int wc, int fr_in, int fq_in) const {
;     ...
;         for (int i = 0; i < 16; ++i) { const int ai = i >> 3, m = (i >> 1) & 3, bj = i & 1; const int n = col0 + bj * 128;
;             const u32x4 gq = *(const u32x4*)(proj + (size_t)(row0 + ai * 128 + m * 16) * NC1 + C_MG + (n >> 7) * 256 + (n & 127));
;             acc[ai][bj][m][0][0] *= bf_lo(gq.x); acc[ai][bj][m][0][1] *= bf_hi(gq.x); acc[ai][bj][m][0][2] *= bf_lo(gq.y); acc[ai][bj][m][0][3] *= bf_hi(gq.y);
;             acc[ai][bj][m][1][0] *= bf_lo(gq.z); acc[ai][bj][m][1][1] *= bf_hi(gq.z); acc[ai][bj][m][1][2] *= bf_lo(gq.w); acc[ai][bj][m][1][3] *= bf_hi(gq.w); }
	v_lshlrev_b32_e32 v128, 16, v136
	v_and_b32_e32 v129, 0xffff0000, v136
	v_lshlrev_b32_e32 v130, 16, v137
	v_and_b32_e32 v131, 0xffff0000, v137
	v_pk_mul_f32 v[60:61], v[60:61], v[128:129]
	v_pk_mul_f32 v[62:63], v[62:63], v[130:131]
	v_lshlrev_b32_e32 v128, 16, v138
	v_and_b32_e32 v129, 0xffff0000, v138
	v_lshlrev_b32_e32 v130, 16, v139
	v_and_b32_e32 v131, 0xffff0000, v139
	v_pk_mul_f32 v[56:57], v[56:57], v[128:129]
	v_pk_mul_f32 v[58:59], v[58:59], v[130:131]
	s_waitcnt vmcnt(13)
	v_lshlrev_b32_e32 v128, 16, v140
	v_and_b32_e32 v129, 0xffff0000, v140
	v_lshlrev_b32_e32 v130, 16, v141
	v_and_b32_e32 v131, 0xffff0000, v141
	v_pk_mul_f32 v[116:117], v[116:117], v[128:129]
	v_pk_mul_f32 v[118:119], v[118:119], v[130:131]
	v_lshlrev_b32_e32 v128, 16, v142
	v_and_b32_e32 v129, 0xffff0000, v142
	v_lshlrev_b32_e32 v130, 16, v143
	v_and_b32_e32 v131, 0xffff0000, v143
	v_pk_mul_f32 v[112:113], v[112:113], v[128:129]
	v_pk_mul_f32 v[114:115], v[114:115], v[130:131]
	s_waitcnt vmcnt(12)
	v_lshlrev_b32_e32 v128, 16, v144
	v_and_b32_e32 v129, 0xffff0000, v144
	v_lshlrev_b32_e32 v130, 16, v145
	v_and_b32_e32 v131, 0xffff0000, v145
	v_pk_mul_f32 v[52:53], v[52:53], v[128:129]
	v_pk_mul_f32 v[54:55], v[54:55], v[130:131]
	v_lshlrev_b32_e32 v128, 16, v146
	v_and_b32_e32 v129, 0xffff0000, v146
	v_lshlrev_b32_e32 v130, 16, v147
	v_and_b32_e32 v131, 0xffff0000, v147
	v_pk_mul_f32 v[48:49], v[48:49], v[128:129]
	v_pk_mul_f32 v[50:51], v[50:51], v[130:131]
	s_waitcnt vmcnt(11)
	v_lshlrev_b32_e32 v128, 16, v148
	v_and_b32_e32 v129, 0xffff0000, v148
	v_lshlrev_b32_e32 v130, 16, v149
	v_and_b32_e32 v131, 0xffff0000, v149
	v_pk_mul_f32 v[108:109], v[108:109], v[128:129]
	v_pk_mul_f32 v[110:111], v[110:111], v[130:131]
	v_lshlrev_b32_e32 v128, 16, v150
	v_and_b32_e32 v129, 0xffff0000, v150
	v_lshlrev_b32_e32 v130, 16, v151
	v_and_b32_e32 v131, 0xffff0000, v151
	v_pk_mul_f32 v[104:105], v[104:105], v[128:129]
	v_pk_mul_f32 v[106:107], v[106:107], v[130:131]
	s_waitcnt vmcnt(10)
	v_lshlrev_b32_e32 v128, 16, v152
	v_and_b32_e32 v129, 0xffff0000, v152
	v_lshlrev_b32_e32 v130, 16, v153
	v_and_b32_e32 v131, 0xffff0000, v153
	v_pk_mul_f32 v[44:45], v[44:45], v[128:129]
	v_pk_mul_f32 v[46:47], v[46:47], v[130:131]
	v_lshlrev_b32_e32 v128, 16, v154
	v_and_b32_e32 v129, 0xffff0000, v154
	v_lshlrev_b32_e32 v130, 16, v155
	v_and_b32_e32 v131, 0xffff0000, v155
	v_pk_mul_f32 v[40:41], v[40:41], v[128:129]
	v_pk_mul_f32 v[42:43], v[42:43], v[130:131]
	s_waitcnt vmcnt(9)
	v_lshlrev_b32_e32 v128, 16, v156
	v_and_b32_e32 v129, 0xffff0000, v156
	v_lshlrev_b32_e32 v130, 16, v157
	v_and_b32_e32 v131, 0xffff0000, v157
	v_pk_mul_f32 v[100:101], v[100:101], v[128:129]
	v_pk_mul_f32 v[102:103], v[102:103], v[130:131]
	v_lshlrev_b32_e32 v128, 16, v158
	v_and_b32_e32 v129, 0xffff0000, v158
	v_lshlrev_b32_e32 v130, 16, v159
	v_and_b32_e32 v131, 0xffff0000, v159
	v_pk_mul_f32 v[96:97], v[96:97], v[128:129]
	v_pk_mul_f32 v[98:99], v[98:99], v[130:131]
	s_waitcnt vmcnt(8)
	v_lshlrev_b32_e32 v128, 16, v160
	v_and_b32_e32 v129, 0xffff0000, v160
	v_lshlrev_b32_e32 v130, 16, v161
	v_and_b32_e32 v131, 0xffff0000, v161
	v_pk_mul_f32 v[36:37], v[36:37], v[128:129]
	v_pk_mul_f32 v[38:39], v[38:39], v[130:131]
	v_lshlrev_b32_e32 v128, 16, v162
	v_and_b32_e32 v129, 0xffff0000, v162
	v_lshlrev_b32_e32 v130, 16, v163
	v_and_b32_e32 v131, 0xffff0000, v163
	v_pk_mul_f32 v[32:33], v[32:33], v[128:129]
	v_pk_mul_f32 v[34:35], v[34:35], v[130:131]
	s_waitcnt vmcnt(7)
; __device__ __forceinline__ float bf_lo(unsigned u) { return __uint_as_float(u << 16); }
; __device__ __forceinline__ float bf_hi(unsigned u) { return __uint_as_float(u & 0xffff0000u); }
;     __device__ __forceinline__ void mid(f32x4 (&acc)[2][2][4][2], const pg8::Unit& u, int wr, int wc, int fr_in, int fq_in) const {
;     ...
;         for (int i = 0; i < 16; ++i) { const int ai = i >> 3, m = (i >> 1) & 3, bj = i & 1; const int n = col0 + bj * 128;
;             const u32x4 gq = *(const u32x4*)(proj + (size_t)(row0 + ai * 128 + m * 16) * NC1 + C_MG + (n >> 7) * 256 + (n & 127));
;             acc[ai][bj][m][0][0] *= bf_lo(gq.x); acc[ai][bj][m][0][1] *= bf_hi(gq.x); acc[ai][bj][m][0][2] *= bf_lo(gq.y); acc[ai][bj][m][0][3] *= bf_hi(gq.y);
;             acc[ai][bj][m][1][0] *= bf_lo(gq.z); acc[ai][bj][m][1][1] *= bf_hi(gq.z); acc[ai][bj][m][1][2] *= bf_lo(gq.w); acc[ai][bj][m][1][3] *= bf_hi(gq.w); }
	v_lshlrev_b32_e32 v128, 16, v164
	v_and_b32_e32 v129, 0xffff0000, v164
	v_lshlrev_b32_e32 v130, 16, v165
	v_and_b32_e32 v131, 0xffff0000, v165
	v_pk_mul_f32 v[92:93], v[92:93], v[128:129]
	v_pk_mul_f32 v[94:95], v[94:95], v[130:131]
	v_lshlrev_b32_e32 v128, 16, v166
	v_and_b32_e32 v129, 0xffff0000, v166
	v_lshlrev_b32_e32 v130, 16, v167
	v_and_b32_e32 v131, 0xffff0000, v167
	v_pk_mul_f32 v[88:89], v[88:89], v[128:129]
	v_pk_mul_f32 v[90:91], v[90:91], v[130:131]
	s_waitcnt vmcnt(6)
	v_lshlrev_b32_e32 v128, 16, v168
	v_and_b32_e32 v129, 0xffff0000, v168
	v_lshlrev_b32_e32 v130, 16, v169
	v_and_b32_e32 v131, 0xffff0000, v169
	v_pk_mul_f32 v[28:29], v[28:29], v[128:129]
	v_pk_mul_f32 v[30:31], v[30:31], v[130:131]
	v_lshlrev_b32_e32 v128, 16, v170
	v_and_b32_e32 v129, 0xffff0000, v170
	v_lshlrev_b32_e32 v130, 16, v171
	v_and_b32_e32 v131, 0xffff0000, v171
	v_pk_mul_f32 v[24:25], v[24:25], v[128:129]
	v_pk_mul_f32 v[26:27], v[26:27], v[130:131]
	s_waitcnt vmcnt(5)
	v_lshlrev_b32_e32 v128, 16, v172
	v_and_b32_e32 v129, 0xffff0000, v172
	v_lshlrev_b32_e32 v130, 16, v173
	v_and_b32_e32 v131, 0xffff0000, v173
	v_pk_mul_f32 v[84:85], v[84:85], v[128:129]
	v_pk_mul_f32 v[86:87], v[86:87], v[130:131]
	v_lshlrev_b32_e32 v128, 16, v174
	v_and_b32_e32 v129, 0xffff0000, v174
	v_lshlrev_b32_e32 v130, 16, v175
	v_and_b32_e32 v131, 0xffff0000, v175
	v_pk_mul_f32 v[80:81], v[80:81], v[128:129]
	v_pk_mul_f32 v[82:83], v[82:83], v[130:131]
	s_waitcnt vmcnt(4)
	v_lshlrev_b32_e32 v128, 16, v192
	v_and_b32_e32 v129, 0xffff0000, v192
	v_lshlrev_b32_e32 v130, 16, v193
	v_and_b32_e32 v131, 0xffff0000, v193
	v_pk_mul_f32 v[20:21], v[20:21], v[128:129]
	v_pk_mul_f32 v[22:23], v[22:23], v[130:131]
	v_lshlrev_b32_e32 v128, 16, v194
	v_and_b32_e32 v129, 0xffff0000, v194
	v_lshlrev_b32_e32 v130, 16, v195
	v_and_b32_e32 v131, 0xffff0000, v195
	v_pk_mul_f32 v[16:17], v[16:17], v[128:129]
	v_pk_mul_f32 v[18:19], v[18:19], v[130:131]
	s_waitcnt vmcnt(3)
	v_lshlrev_b32_e32 v128, 16, v196
	v_and_b32_e32 v129, 0xffff0000, v196
	v_lshlrev_b32_e32 v130, 16, v197
	v_and_b32_e32 v131, 0xffff0000, v197
	v_pk_mul_f32 v[76:77], v[76:77], v[128:129]
	v_pk_mul_f32 v[78:79], v[78:79], v[130:131]
	v_lshlrev_b32_e32 v128, 16, v198
	v_and_b32_e32 v129, 0xffff0000, v198
	v_lshlrev_b32_e32 v130, 16, v199
	v_and_b32_e32 v131, 0xffff0000, v199
	v_pk_mul_f32 v[72:73], v[72:73], v[128:129]
	v_pk_mul_f32 v[74:75], v[74:75], v[130:131]
	s_waitcnt vmcnt(2)
	v_lshlrev_b32_e32 v128, 16, v200
	v_and_b32_e32 v129, 0xffff0000, v200
	v_lshlrev_b32_e32 v130, 16, v201
	v_and_b32_e32 v131, 0xffff0000, v201
	v_pk_mul_f32 v[12:13], v[12:13], v[128:129]
	v_pk_mul_f32 v[14:15], v[14:15], v[130:131]
	v_lshlrev_b32_e32 v128, 16, v202
	v_and_b32_e32 v129, 0xffff0000, v202
	v_lshlrev_b32_e32 v130, 16, v203
	v_and_b32_e32 v131, 0xffff0000, v203
	v_pk_mul_f32 v[8:9], v[8:9], v[128:129]
	v_pk_mul_f32 v[10:11], v[10:11], v[130:131]
	s_waitcnt vmcnt(1)
	v_lshlrev_b32_e32 v128, 16, v204
	v_and_b32_e32 v129, 0xffff0000, v204
	v_lshlrev_b32_e32 v130, 16, v205
	v_and_b32_e32 v131, 0xffff0000, v205
	v_pk_mul_f32 v[68:69], v[68:69], v[128:129]
	v_pk_mul_f32 v[70:71], v[70:71], v[130:131]
	v_lshlrev_b32_e32 v128, 16, v206
	v_and_b32_e32 v129, 0xffff0000, v206
	v_lshlrev_b32_e32 v130, 16, v207
	v_and_b32_e32 v131, 0xffff0000, v207
	v_pk_mul_f32 v[64:65], v[64:65], v[128:129]
	v_pk_mul_f32 v[66:67], v[66:67], v[130:131]
	s_waitcnt vmcnt(0)
	v_lshlrev_b32_e32 v128, 16, v208
	v_and_b32_e32 v129, 0xffff0000, v208
	v_lshlrev_b32_e32 v130, 16, v209
	v_and_b32_e32 v131, 0xffff0000, v209
	v_pk_mul_f32 v[4:5], v[4:5], v[128:129]
	v_pk_mul_f32 v[6:7], v[6:7], v[130:131]
	v_lshlrev_b32_e32 v128, 16, v210
	v_and_b32_e32 v129, 0xffff0000, v210
	v_lshlrev_b32_e32 v130, 16, v211
	v_and_b32_e32 v131, 0xffff0000, v211
	v_pk_mul_f32 v[0:1], v[0:1], v[128:129]
	v_pk_mul_f32 v[2:3], v[2:3], v[130:131]
	s_branch .LBB0_300
